# v20 + same v_pk_mov_b32 broadcast init at the three other attention kv-step sites (SWA loop and the two other MLA-phase loops)
# baseline (speedup 1.0000x reference)
; #define MFMA32(a, b, c) __builtin_amdgcn_mfma_f32_32x32x16_bf16((a), (b), (c), 0, 0, 0)
; DI unsigned pack2(float a, float b) { hwf2_t f = {a, b}; return __builtin_bit_cast(unsigned, __builtin_convertvector(f, hwbf2_t)); }
; template <int DQK, bool WINDOW>
; DI void attn_item(char* smem, const bf16_t* __restrict__ Q, const bf16_t* __restrict__ K, const bf16_t* __restrict__ VT,
;                   int qh, int kvh, int b, int q0, bool has_sink, float sink_l2, bf16_t* __restrict__ Y, int ycol) {
;     ...
;     float rsum = 0;
; #pragma unroll
;     for (int i = 0; i < 16; ++i) { s0[i] = __builtin_amdgcn_exp2f(s0[i]); s1[i] = __builtin_amdgcn_exp2f(s1[i]); rsum += s0[i] + s1[i]; }
;     rsum += __shfl_xor(rsum, 32, 64);
;     lsum += rsum;
; #pragma unroll
;     for (int mt = 0; mt < 2; ++mt) {
; #pragma unroll
;       for (int s = 0; s < 2; ++s) {
;         union { bf16x8 v; unsigned u[4]; } pk;
;         if (mt == 0) {
;           pk.u[0] = pack2(s0[8 * s + 0], s0[8 * s + 1]); pk.u[1] = pack2(s0[8 * s + 2], s0[8 * s + 3]);
;           pk.u[2] = pack2(s0[8 * s + 4], s0[8 * s + 5]); pk.u[3] = pack2(s0[8 * s + 6], s0[8 * s + 7]);
;         } else {
;           pk.u[0] = pack2(s1[8 * s + 0], s1[8 * s + 1]); pk.u[1] = pack2(s1[8 * s + 2], s1[8 * s + 3]);
;           pk.u[2] = pack2(s1[8 * s + 4], s1[8 * s + 5]); pk.u[3] = pack2(s1[8 * s + 6], s1[8 * s + 7]);
;         }
;         const int base = mt * 32 + s * 16 + 4 * h;
;         union { bf16x8 v; uint2 u[2]; } va, vb;
;         va.u[0] = *(const uint2*)(sV + r * VSTR + base);
;         va.u[1] = *(const uint2*)(sV + r * VSTR + base + 8);
;         vb.u[0] = *(const uint2*)(sV + (32 + r) * VSTR + base);
;         vb.u[1] = *(const uint2*)(sV + (32 + r) * VSTR + base + 8);
;         o0 = MFMA32(va.v, pk.v, o0);
;         o1 = MFMA32(vb.v, pk.v, o1);
;       }
;     }
.LBB0_147:
	s_nop 6
	v_exp_f32_e32 v18, v18
	s_nop 1
	v_exp_f32_e32 v117, v2
	v_exp_f32_e32 v19, v19
	v_exp_f32_e32 v118, v3
	v_exp_f32_e32 v20, v20
	v_exp_f32_e32 v119, v4
	v_exp_f32_e32 v4, v21
	v_exp_f32_e32 v120, v5
	v_add_f32_e32 v2, v18, v117
	v_exp_f32_e32 v5, v22
	v_exp_f32_e32 v121, v6
	v_add_f32_e32 v2, 0, v2
	v_add_f32_e32 v3, v19, v118
	v_exp_f32_e32 v21, v23
	v_exp_f32_e32 v122, v7
	v_add_f32_e32 v2, v3, v2
	v_add_f32_e32 v3, v20, v119
	v_exp_f32_e32 v7, v24
	v_exp_f32_e32 v95, v8
	v_exp_f32_e32 v6, v25
	v_exp_f32_e32 v94, v9
	v_add_f32_e32 v2, v3, v2
	v_add_f32_e32 v3, v4, v120
	v_add_f32_e32 v2, v3, v2
	v_add_f32_e32 v3, v5, v121
	v_exp_f32_e32 v63, v26
	v_exp_f32_e32 v97, v10
	v_exp_f32_e32 v62, v27
	v_exp_f32_e32 v96, v11
	v_add_f32_e32 v2, v3, v2
	v_add_f32_e32 v3, v21, v122
	v_add_f32_e32 v22, v3, v2
	v_pk_add_f32 v[2:3], v[6:7], v[94:95]
	v_exp_f32_e32 v65, v28
	v_exp_f32_e32 v99, v12
	v_exp_f32_e32 v64, v29
	v_exp_f32_e32 v98, v13
	v_add_f32_e32 v3, v3, v22
	v_add_f32_e32 v8, v2, v3
	v_pk_add_f32 v[2:3], v[62:63], v[96:97]
	v_exp_f32_e32 v91, v30
	v_exp_f32_e32 v101, v14
	v_exp_f32_e32 v90, v31
	v_exp_f32_e32 v100, v15
	v_add_f32_e32 v3, v3, v8
	v_add_f32_e32 v8, v2, v3
	v_pk_add_f32 v[2:3], v[64:65], v[98:99]
	v_exp_f32_e32 v93, v32
	v_exp_f32_e32 v115, v16
	v_exp_f32_e32 v92, v33
	v_exp_f32_e32 v114, v17
	v_add_f32_e32 v3, v3, v8
	v_add_f32_e32 v8, v2, v3
	v_pk_add_f32 v[2:3], v[90:91], v[100:101]
	v_pk_mov_b32 v[6:7], v[6:7], v[6:7] op_sel:[1,0]
	v_add_f32_e32 v3, v3, v8
	v_add_f32_e32 v8, v2, v3
	v_pk_add_f32 v[2:3], v[92:93], v[114:115]
	v_pk_mov_b32 v[62:63], v[62:63], v[62:63] op_sel:[1,0]
	v_add_f32_e32 v3, v3, v8
	v_add_f32_e32 v2, v2, v3
	ds_bpermute_b32 v3, v109, v2
	v_pk_mov_b32 v[64:65], v[64:65], v[64:65] op_sel:[1,0]
	v_cvt_pk_bf16_f32 v62, v62, v63
	v_cvt_pk_bf16_f32 v63, v64, v65
	v_pk_mov_b32 v[64:65], v[90:91], v[90:91] op_sel:[1,0]
	s_waitcnt lgkmcnt(0)
	v_add_f32_e32 v123, v2, v3
	v_lshlrev_b32_e32 v2, 6, v110
	v_sub_u32_e32 v8, v57, v2
	v_lshl_add_u32 v116, v112, 3, v8
	v_add_u32_e32 v57, 0x3000, v116
	v_add_u32_e32 v124, 0x4000, v116
	v_cvt_pk_bf16_f32 v3, v20, v4
	v_cvt_pk_bf16_f32 v4, v5, v21
	v_cvt_pk_bf16_f32 v5, v6, v7
	ds_read2_b64 v[6:9], v57 offset0:128 offset1:130
	ds_read2_b64 v[58:61], v57 offset0:132 offset1:134
	ds_read2_b64 v[10:13], v124 offset0:192 offset1:194
	v_pk_mov_b32 v[90:91], v[92:93], v[92:93] op_sel:[1,0]
	v_cvt_pk_bf16_f32 v2, v18, v19
	v_cvt_pk_bf16_f32 v64, v64, v65
	v_cvt_pk_bf16_f32 v65, v90, v91
	ds_read2_b64 v[90:93], v124 offset0:196 offset1:198
	s_waitcnt lgkmcnt(3)
	v_mfma_f32_32x32x16_bf16 v[18:33], v[6:9], v[2:5], 0
	v_add_u32_e32 v55, 0xc0, v55
	v_mad_i64_i32 v[50:51], s[2:3], v55, s0, v[50:51]
	s_waitcnt lgkmcnt(1)
	v_mfma_f32_32x32x16_bf16 v[2:17], v[10:13], v[2:5], 0
	s_waitcnt lgkmcnt(0)
	v_mfma_f32_32x32x16_bf16 v[2:17], v[90:93], v[62:65], v[2:17]
	v_mfma_f32_32x32x16_bf16 v[18:33], v[58:61], v[62:65], v[18:33]
	v_pk_mov_b32 v[62:63], v[94:95], v[94:95] op_sel:[1,0]
	v_cvt_pk_bf16_f32 v58, v117, v118
	v_cvt_pk_bf16_f32 v61, v62, v63
	ds_read2_b64 v[62:65], v57 offset0:136 offset1:138
	ds_read2_b64 v[90:93], v124 offset0:200 offset1:202
	v_cvt_pk_bf16_f32 v59, v119, v120
	v_cvt_pk_bf16_f32 v60, v121, v122
	s_waitcnt lgkmcnt(0)
	s_nop 0
	v_mfma_f32_32x32x16_bf16 v[2:17], v[90:93], v[58:61], v[2:17]
	v_mfma_f32_32x32x16_bf16 v[18:33], v[62:65], v[58:61], v[18:33]
	v_pk_mov_b32 v[58:59], v[96:97], v[96:97] op_sel:[1,0]
	v_pk_mov_b32 v[60:61], v[98:99], v[98:99] op_sel:[1,0]
	v_cvt_pk_bf16_f32 v58, v58, v59
	v_cvt_pk_bf16_f32 v59, v60, v61
	v_pk_mov_b32 v[60:61], v[100:101], v[100:101] op_sel:[1,0]
	v_pk_mov_b32 v[62:63], v[114:115], v[114:115] op_sel:[1,0]
	v_cvt_pk_bf16_f32 v60, v60, v61
	v_cvt_pk_bf16_f32 v61, v62, v63
	ds_read2_b64 v[62:65], v57 offset0:140 offset1:142
	ds_read2_b64 v[90:93], v124 offset0:204 offset1:206
	s_waitcnt lgkmcnt(0)
	v_mfma_f32_32x32x16_bf16 v[2:17], v[90:93], v[58:61], v[2:17]
	global_load_dwordx4 v[90:93], v[50:51], off
	v_add_u32_e32 v50, 0xc0, v56
	v_mad_i64_i32 v[48:49], s[2:3], v50, s0, v[48:49]
	global_load_dwordx4 v[94:97], v[48:49], off
	global_load_dwordx4 v[98:101], v[46:47], off offset:384
	v_add_f32_e32 v115, 0, v123
	v_mfma_f32_32x32x16_bf16 v[18:33], v[62:65], v[58:61], v[18:33]
	s_barrier
; #define MFMA32(a, b, c) __builtin_amdgcn_mfma_f32_32x32x16_bf16((a), (b), (c), 0, 0, 0)
; DI int crow(int reg, int h) { return (reg & 3) + 8 * (reg >> 2) + 4 * h; }
; #define ALOAD(i) { const int kk0 = TILE_K0(i); \
;     kr0 = *(const uint4*)(Kb + (size_t)(kk0 + krow0) * DQK + kcc0 * 8); \
;     if (K2) kr1 = *(const uint4*)(Kb + (size_t)(kk0 + krow1) * DQK + kcc1 * 8); \
;     vr0 = *(const uint4*)(Vb + (size_t)vrow0 * TT + kk0 + vcc0 * 8); }
; template <int DQK, bool WINDOW>
; DI void attn_item(char* smem, const bf16_t* __restrict__ Q, const bf16_t* __restrict__ K, const bf16_t* __restrict__ VT,
;                   int qh, int kvh, int b, int q0, bool has_sink, float sink_l2, bf16_t* __restrict__ Y, int ycol) {
;     ...
;     __syncthreads();
;     ASTORE((it + 1) & 1)
;     __builtin_amdgcn_sched_barrier(0);
;     ALOAD(min(it + 2, ntiles - 1))
;     __builtin_amdgcn_sched_barrier(0);
;     sK = (bf16_t*)smem + (it & 1) * BUFE;
;     sV = sK + 64 * KSTR;
;     f32x16 s0, s1;
;     const float ninit = -m;
; #pragma unroll
;     for (int i = 0; i < 16; ++i) { s0[i] = ninit; s1[i] = ninit; }
; #pragma unroll
;     for (int ks = 0; ks < KS; ++ks) {
;       bf16x8 a0 = *(const bf16x8*)(sK + r * KSTR + ks * 16 + 8 * h);
;       bf16x8 a1 = *(const bf16x8*)(sK + (32 + r) * KSTR + ks * 16 + 8 * h);
;       s0 = MFMA32(a0, qf[ks], s0);
;       s1 = MFMA32(a1, qf[ks], s1);
;     }
;     if (WINDOW && k0 >= CTXL) {
; #pragma unroll
;       for (int i = 0; i < 16; ++i) {
;         const int kp = k0 + crow(i, h);
;         if (abs(qpos - kp) > 128) s0[i] = -1e30f;
;         if (abs(qpos - kp - 32) > 128) s1[i] = -1e30f;
;       }
;     }
;     int mxb = max(__float_as_int(s0[0]), __float_as_int(s1[0]));
; #pragma unroll
;     for (int i = 1; i < 16; ++i) mxb = max(mxb, max(__float_as_int(s0[i]), __float_as_int(s1[i])));
;     if (__any((it == 0) || (mxb > 0x41000000))) {
;       float mx = -1e30f;
; #pragma unroll
;       for (int i = 0; i < 16; ++i) mx = fmaxf(mx, fmaxf(s0[i], s1[i]));
;       mx = fmaxf(mx, __shfl_xor(mx, 32, 64));
;       const float delta = (it == 0) ? mx : fmaxf(mx, 0.f);
;       const float alpha = (it == 0) ? 1.f : __builtin_amdgcn_exp2f(-delta);
;       m += delta;
;       lsum *= alpha;
; #pragma unroll
;       for (int i = 0; i < 16; ++i) { o0[i] *= alpha; o1[i] *= alpha; s0[i] -= delta; s1[i] -= delta; }
;     }
	s_waitcnt vmcnt(5)
	ds_write_b128 v52, v[34:37]
	s_waitcnt vmcnt(4)
	ds_write_b128 v53, v[38:41]
	s_waitcnt vmcnt(3)
	ds_write_b128 v54, v[42:45] offset:13312
	ds_read_b128 v[118:121], v113 offset:22528
	v_xor_b32_e32 v34, 0x80000000, v111
	v_mov_b32_e32 v35, v34
	v_pk_mov_b32 v[36:37], v[34:35], v[34:35] op_sel:[0,0] op_sel_hi:[0,0]
	v_pk_mov_b32 v[38:39], v[34:35], v[34:35] op_sel:[0,0] op_sel_hi:[0,0]
	v_pk_mov_b32 v[40:41], v[34:35], v[34:35] op_sel:[0,0] op_sel_hi:[0,0]
	v_pk_mov_b32 v[42:43], v[34:35], v[34:35] op_sel:[0,0] op_sel_hi:[0,0]
	v_pk_mov_b32 v[44:45], v[34:35], v[34:35] op_sel:[0,0] op_sel_hi:[0,0]
	v_pk_mov_b32 v[46:47], v[34:35], v[34:35] op_sel:[0,0] op_sel_hi:[0,0]
	v_pk_mov_b32 v[48:49], v[34:35], v[34:35] op_sel:[0,0] op_sel_hi:[0,0]
	s_mov_b32 s2, 0x41000000
	s_waitcnt lgkmcnt(0)
	v_mfma_f32_32x32x16_bf16 v[50:65], v[118:121], v[66:69], v[34:49]
	ds_read_b128 v[118:121], v113 offset:29184
	s_waitcnt lgkmcnt(0)
	v_mfma_f32_32x32x16_bf16 v[34:49], v[118:121], v[66:69], v[34:49]
	ds_read_b128 v[118:121], v113 offset:22560
	s_waitcnt lgkmcnt(0)
	v_mfma_f32_32x32x16_bf16 v[50:65], v[118:121], v[70:73], v[50:65]
	ds_read_b128 v[118:121], v113 offset:29216
	s_waitcnt lgkmcnt(0)
	v_mfma_f32_32x32x16_bf16 v[34:49], v[118:121], v[70:73], v[34:49]
	ds_read_b128 v[118:121], v113 offset:22592
	s_waitcnt lgkmcnt(0)
	v_mfma_f32_32x32x16_bf16 v[50:65], v[118:121], v[74:77], v[50:65]
	ds_read_b128 v[118:121], v113 offset:29248
	s_waitcnt lgkmcnt(0)
	v_mfma_f32_32x32x16_bf16 v[34:49], v[118:121], v[74:77], v[34:49]
	ds_read_b128 v[118:121], v113 offset:22624
	s_waitcnt lgkmcnt(0)
	v_mfma_f32_32x32x16_bf16 v[50:65], v[118:121], v[78:81], v[50:65]
	ds_read_b128 v[118:121], v113 offset:29280
	s_waitcnt lgkmcnt(0)
	v_mfma_f32_32x32x16_bf16 v[34:49], v[118:121], v[78:81], v[34:49]
	ds_read_b128 v[118:121], v113 offset:22656
	s_waitcnt lgkmcnt(0)
	v_mfma_f32_32x32x16_bf16 v[50:65], v[118:121], v[82:85], v[50:65]
	ds_read_b128 v[118:121], v113 offset:29312
	s_waitcnt lgkmcnt(0)
	v_mfma_f32_32x32x16_bf16 v[34:49], v[118:121], v[82:85], v[34:49]
	ds_read_b128 v[118:121], v113 offset:22688
	s_waitcnt lgkmcnt(0)
	v_mfma_f32_32x32x16_bf16 v[50:65], v[118:121], v[86:89], v[50:65]
	ds_read_b128 v[118:121], v113 offset:29344
	s_waitcnt lgkmcnt(0)
	v_mfma_f32_32x32x16_bf16 v[34:49], v[118:121], v[86:89], v[34:49]
	s_nop 11
	v_max_i32_e32 v113, v51, v35
	v_max3_i32 v113, v50, v34, v113
	v_max_i32_e32 v114, v52, v36
	v_max_i32_e32 v117, v53, v37
	v_max3_i32 v113, v113, v114, v117
	v_max_i32_e32 v114, v54, v38
	v_max_i32_e32 v117, v55, v39
	v_max3_i32 v113, v113, v114, v117
	v_max_i32_e32 v114, v56, v40
	v_max_i32_e32 v117, v57, v41
	v_max3_i32 v113, v113, v114, v117
	v_max_i32_e32 v114, v58, v42
	v_max_i32_e32 v117, v59, v43
	v_max3_i32 v113, v113, v114, v117
	v_max_i32_e32 v114, v60, v44
	v_max_i32_e32 v117, v61, v45
	v_max3_i32 v113, v113, v114, v117
	v_max_i32_e32 v114, v62, v46
	v_max_i32_e32 v117, v63, v47
	v_max3_i32 v113, v113, v114, v117
	v_max_i32_e32 v114, v64, v48
	v_max_i32_e32 v117, v65, v49
	v_max3_i32 v113, v113, v114, v117
	v_cmp_lt_i32_e32 vcc, s2, v113
	s_cbranch_vccz .LBB0_149
	v_max_f32_e32 v113, v34, v34
	v_max_f32_e32 v114, v50, v50
	v_max_f32_e32 v113, v114, v113
	v_max_f32_e32 v114, v35, v35
	v_max_f32_e32 v117, v51, v51
	v_max_f32_e32 v114, v117, v114
	s_mov_b32 s2, 0xf149f2ca
	v_max3_f32 v113, v113, s2, v114
	v_max_f32_e32 v114, v36, v36
	v_max_f32_e32 v117, v52, v52
	v_max_f32_e32 v114, v117, v114
	v_max_f32_e32 v117, v37, v37
	v_max_f32_e32 v118, v53, v53
	v_max_f32_e32 v117, v118, v117
	v_max3_f32 v113, v113, v114, v117
	v_max_f32_e32 v114, v38, v38
	v_max_f32_e32 v117, v54, v54
	v_max_f32_e32 v114, v117, v114
	v_max_f32_e32 v117, v39, v39
	v_max_f32_e32 v118, v55, v55
	v_max_f32_e32 v117, v118, v117
	v_max3_f32 v113, v113, v114, v117
	v_max_f32_e32 v114, v40, v40
	v_max_f32_e32 v117, v56, v56
	v_max_f32_e32 v114, v117, v114
	v_max_f32_e32 v117, v41, v41
	v_max_f32_e32 v118, v57, v57
	v_max_f32_e32 v117, v118, v117
	v_max3_f32 v113, v113, v114, v117
	v_max_f32_e32 v114, v42, v42
	v_max_f32_e32 v117, v58, v58
	v_max_f32_e32 v114, v117, v114
	v_max_f32_e32 v117, v43, v43
	v_max_f32_e32 v118, v59, v59
	v_max_f32_e32 v117, v118, v117
	v_max3_f32 v113, v113, v114, v117
	v_max_f32_e32 v114, v44, v44
	v_max_f32_e32 v117, v60, v60
	v_max_f32_e32 v114, v117, v114
	v_max_f32_e32 v117, v45, v45
	v_max_f32_e32 v118, v61, v61
	v_max_f32_e32 v117, v118, v117
	v_max3_f32 v113, v113, v114, v117
	v_max_f32_e32 v114, v46, v46
	v_max_f32_e32 v117, v62, v62
	v_max_f32_e32 v114, v117, v114
	v_max_f32_e32 v117, v47, v47
	v_max_f32_e32 v118, v63, v63
	v_max_f32_e32 v117, v118, v117
	v_max3_f32 v113, v113, v114, v117
	v_max_f32_e32 v114, v48, v48
	v_max_f32_e32 v117, v64, v64
	v_max_f32_e32 v114, v117, v114
	v_max_f32_e32 v117, v49, v49
	v_max_f32_e32 v118, v65, v65
	v_max_f32_e32 v117, v118, v117
	v_max3_f32 v113, v113, v114, v117
	ds_bpermute_b32 v114, v109, v113
	s_waitcnt lgkmcnt(0)
	v_max3_f32 v113, v113, v114, 0
	v_exp_f32_e64 v114, -v113
	v_add_f32_e32 v111, v111, v113
	v_sub_f32_e32 v65, v65, v113
	v_sub_f32_e32 v64, v64, v113
	v_pk_mul_f32 v[32:33], v[32:33], v[114:115] op_sel_hi:[1,0]
	v_pk_mul_f32 v[30:31], v[30:31], v[114:115] op_sel_hi:[1,0]
	v_pk_mul_f32 v[28:29], v[28:29], v[114:115] op_sel_hi:[1,0]
	v_pk_mul_f32 v[26:27], v[26:27], v[114:115] op_sel_hi:[1,0]
	v_pk_mul_f32 v[24:25], v[24:25], v[114:115] op_sel_hi:[1,0]
	v_pk_mul_f32 v[22:23], v[22:23], v[114:115] op_sel_hi:[1,0]
	v_pk_mul_f32 v[20:21], v[20:21], v[114:115] op_sel_hi:[1,0]
	v_pk_mul_f32 v[18:19], v[18:19], v[114:115] op_sel_hi:[1,0]
	v_pk_mul_f32 v[16:17], v[16:17], v[114:115] op_sel_hi:[1,0]
	v_pk_mul_f32 v[14:15], v[14:15], v[114:115] op_sel_hi:[1,0]
	v_pk_mul_f32 v[12:13], v[12:13], v[114:115] op_sel_hi:[1,0]
	v_pk_mul_f32 v[10:11], v[10:11], v[114:115] op_sel_hi:[1,0]
	v_pk_mul_f32 v[8:9], v[8:9], v[114:115] op_sel_hi:[1,0]
	v_pk_mul_f32 v[6:7], v[6:7], v[114:115] op_sel_hi:[1,0]
	v_pk_mul_f32 v[4:5], v[4:5], v[114:115] op_sel_hi:[1,0]
	v_pk_mul_f32 v[2:3], v[2:3], v[114:115] op_sel_hi:[1,0]
	v_sub_f32_e32 v63, v63, v113
	v_sub_f32_e32 v62, v62, v113
	v_sub_f32_e32 v61, v61, v113
	v_sub_f32_e32 v60, v60, v113
	v_sub_f32_e32 v59, v59, v113
	v_sub_f32_e32 v58, v58, v113
	v_sub_f32_e32 v57, v57, v113
	v_sub_f32_e32 v56, v56, v113
	v_sub_f32_e32 v55, v55, v113
	v_sub_f32_e32 v54, v54, v113
	v_sub_f32_e32 v53, v53, v113
	v_sub_f32_e32 v52, v52, v113
	v_sub_f32_e32 v51, v51, v113
	v_sub_f32_e32 v50, v50, v113
	v_sub_f32_e32 v49, v49, v113
	v_sub_f32_e32 v48, v48, v113
	v_sub_f32_e32 v47, v47, v113
	v_sub_f32_e32 v46, v46, v113
	v_sub_f32_e32 v45, v45, v113
	v_sub_f32_e32 v44, v44, v113
	v_sub_f32_e32 v43, v43, v113
	v_sub_f32_e32 v42, v42, v113
	v_sub_f32_e32 v41, v41, v113
	v_sub_f32_e32 v40, v40, v113
	v_sub_f32_e32 v39, v39, v113
	v_sub_f32_e32 v38, v38, v113
	v_sub_f32_e32 v37, v37, v113
	v_sub_f32_e32 v36, v36, v113
	v_sub_f32_e32 v35, v35, v113
	v_sub_f32_e32 v34, v34, v113
	v_mul_f32_e32 v115, v115, v114

; #define MFMA32(a, b, c) __builtin_amdgcn_mfma_f32_32x32x16_bf16((a), (b), (c), 0, 0, 0)
; DI int crow(int reg, int h) { return (reg & 3) + 8 * (reg >> 2) + 4 * h; }
; #define ALOAD(i) { const int kk0 = TILE_K0(i); \
;     kr0 = *(const uint4*)(Kb + (size_t)(kk0 + krow0) * DQK + kcc0 * 8); \
;     if (K2) kr1 = *(const uint4*)(Kb + (size_t)(kk0 + krow1) * DQK + kcc1 * 8); \
;     vr0 = *(const uint4*)(Vb + (size_t)vrow0 * TT + kk0 + vcc0 * 8); }
; #define ASTORE(bb) { bf16_t* dK = (bf16_t*)smem + (bb) * BUFE; bf16_t* dV = dK + 64 * KSTR; \
;     *(uint4*)(dK + krow0 * KSTR + kcc0 * 8) = kr0; \
;     if (K2) *(uint4*)(dK + krow1 * KSTR + kcc1 * 8) = kr1; \
;     *(uint4*)(dV + vrow0 * VSTR + vcc0 * 8) = vr0; }
; template <int DQK, bool WINDOW>
; DI void attn_item(char* smem, const bf16_t* __restrict__ Q, const bf16_t* __restrict__ K, const bf16_t* __restrict__ VT,
;                   int qh, int kvh, int b, int q0, bool has_sink, float sink_l2, bf16_t* __restrict__ Y, int ycol) {
;     ...
;   for (int it = 0; it < ntiles; ++it) {
;     const int k0 = TILE_K0(it);
;     __syncthreads();
;     ASTORE((it + 1) & 1)
;     __builtin_amdgcn_sched_barrier(0);
;     ALOAD(min(it + 2, ntiles - 1))
;     __builtin_amdgcn_sched_barrier(0);
;     sK = (bf16_t*)smem + (it & 1) * BUFE;
;     sV = sK + 64 * KSTR;
;     f32x16 s0, s1;
;     const float ninit = -m;
; #pragma unroll
;     for (int i = 0; i < 16; ++i) { s0[i] = ninit; s1[i] = ninit; }
; #pragma unroll
;     for (int ks = 0; ks < KS; ++ks) {
;       bf16x8 a0 = *(const bf16x8*)(sK + r * KSTR + ks * 16 + 8 * h);
;       bf16x8 a1 = *(const bf16x8*)(sK + (32 + r) * KSTR + ks * 16 + 8 * h);
;       s0 = MFMA32(a0, qf[ks], s0);
;       s1 = MFMA32(a1, qf[ks], s1);
;     }
;     if (WINDOW && k0 >= CTXL) {
; #pragma unroll
;       for (int i = 0; i < 16; ++i) {
;         const int kp = k0 + crow(i, h);
;         if (abs(qpos - kp) > 128) s0[i] = -1e30f;
;         if (abs(qpos - kp - 32) > 128) s1[i] = -1e30f;
;       }
;     }
;     int mxb = max(__float_as_int(s0[0]), __float_as_int(s1[0]));
; #pragma unroll
;     for (int i = 1; i < 16; ++i) mxb = max(mxb, max(__float_as_int(s0[i]), __float_as_int(s1[i])));
;     if (__any((it == 0) || (mxb > 0x41000000))) {
.LBB0_151:
	s_add_i32 s2, s3, 1
	s_bitcmp1_b32 s2, 0
	s_cselect_b32 s6, 0x5800, 0
	s_add_i32 s6, s6, 0
	v_lshlrev_b32_e32 v34, 1, v104
	v_add3_u32 v34, s6, v103, v34
	s_barrier
	s_waitcnt vmcnt(2)
	ds_write_b128 v34, v[90:93]
	v_lshlrev_b32_e32 v34, 1, v106
	v_add3_u32 v34, s6, v105, v34
	s_waitcnt vmcnt(1)
	ds_write_b128 v34, v[94:97]
	v_add3_u32 v34, s6, v107, v108
	s_waitcnt vmcnt(0)
	ds_write_b128 v34, v[98:101] offset:13312
	s_bitcmp1_b32 s3, 0
	s_cselect_b32 s3, 0x5800, 0
	s_add_i32 s3, s3, 0
	v_add3_u32 v120, s3, v113, v115
	ds_read_b128 v[116:119], v120
	v_xor_b32_e32 v34, 0x80000000, v111
	v_mov_b32_e32 v35, v34
	v_pk_mov_b32 v[36:37], v[34:35], v[34:35] op_sel:[0,0] op_sel_hi:[0,0]
	v_pk_mov_b32 v[38:39], v[34:35], v[34:35] op_sel:[0,0] op_sel_hi:[0,0]
	v_pk_mov_b32 v[40:41], v[34:35], v[34:35] op_sel:[0,0] op_sel_hi:[0,0]
	v_pk_mov_b32 v[42:43], v[34:35], v[34:35] op_sel:[0,0] op_sel_hi:[0,0]
	v_pk_mov_b32 v[44:45], v[34:35], v[34:35] op_sel:[0,0] op_sel_hi:[0,0]
	v_pk_mov_b32 v[46:47], v[34:35], v[34:35] op_sel:[0,0] op_sel_hi:[0,0]
	v_pk_mov_b32 v[48:49], v[34:35], v[34:35] op_sel:[0,0] op_sel_hi:[0,0]
	s_mov_b32 s6, 0x41000000
	s_waitcnt lgkmcnt(0)
	v_mfma_f32_32x32x16_bf16 v[50:65], v[116:119], v[66:69], v[34:49]
	ds_read_b128 v[116:119], v120 offset:6656
	s_waitcnt lgkmcnt(0)
	v_mfma_f32_32x32x16_bf16 v[34:49], v[116:119], v[66:69], v[34:49]
	ds_read_b128 v[116:119], v120 offset:32
	s_waitcnt lgkmcnt(0)
	v_mfma_f32_32x32x16_bf16 v[50:65], v[116:119], v[70:73], v[50:65]
	ds_read_b128 v[116:119], v120 offset:6688
	s_waitcnt lgkmcnt(0)
	v_mfma_f32_32x32x16_bf16 v[34:49], v[116:119], v[70:73], v[34:49]
	ds_read_b128 v[116:119], v120 offset:64
	s_waitcnt lgkmcnt(0)
	v_mfma_f32_32x32x16_bf16 v[50:65], v[116:119], v[74:77], v[50:65]
	ds_read_b128 v[116:119], v120 offset:6720
	s_waitcnt lgkmcnt(0)
	v_mfma_f32_32x32x16_bf16 v[34:49], v[116:119], v[74:77], v[34:49]
	ds_read_b128 v[116:119], v120 offset:96
	s_waitcnt lgkmcnt(0)
	v_mfma_f32_32x32x16_bf16 v[50:65], v[116:119], v[78:81], v[50:65]
	ds_read_b128 v[116:119], v120 offset:6752
	s_waitcnt lgkmcnt(0)
	v_mfma_f32_32x32x16_bf16 v[34:49], v[116:119], v[78:81], v[34:49]
	ds_read_b128 v[116:119], v120 offset:128
	s_waitcnt lgkmcnt(0)
	v_mfma_f32_32x32x16_bf16 v[50:65], v[116:119], v[82:85], v[50:65]
	ds_read_b128 v[116:119], v120 offset:6784
	s_waitcnt lgkmcnt(0)
	v_mfma_f32_32x32x16_bf16 v[34:49], v[116:119], v[82:85], v[34:49]
	ds_read_b128 v[116:119], v120 offset:160
	s_waitcnt lgkmcnt(0)
	v_mfma_f32_32x32x16_bf16 v[50:65], v[116:119], v[86:89], v[50:65]
	ds_read_b128 v[116:119], v120 offset:6816
	s_waitcnt lgkmcnt(0)
	v_mfma_f32_32x32x16_bf16 v[34:49], v[116:119], v[86:89], v[34:49]
	s_nop 11
	v_max_i32_e32 v116, v51, v35
	v_max3_i32 v116, v50, v34, v116
	v_max_i32_e32 v117, v52, v36
	v_max_i32_e32 v118, v53, v37
	v_max3_i32 v116, v116, v117, v118
	v_max_i32_e32 v117, v54, v38
	v_max_i32_e32 v118, v55, v39
	v_max3_i32 v116, v116, v117, v118
	v_max_i32_e32 v117, v56, v40
	v_max_i32_e32 v118, v57, v41
	v_max3_i32 v116, v116, v117, v118
	v_max_i32_e32 v117, v58, v42
	v_max_i32_e32 v118, v59, v43
	v_max3_i32 v116, v116, v117, v118
	v_max_i32_e32 v117, v60, v44
	v_max_i32_e32 v118, v61, v45
	v_max3_i32 v116, v116, v117, v118
	v_max_i32_e32 v117, v62, v46
	v_max_i32_e32 v118, v63, v47
	v_max3_i32 v116, v116, v117, v118
	v_max_i32_e32 v117, v64, v48
	v_max_i32_e32 v118, v65, v49
	v_max3_i32 v116, v116, v117, v118
	v_cmp_lt_i32_e32 vcc, s6, v116
	s_cbranch_vccz .LBB0_150
; template <int DQK, bool WINDOW>
; DI void attn_item(char* smem, const bf16_t* __restrict__ Q, const bf16_t* __restrict__ K, const bf16_t* __restrict__ VT,
;                   int qh, int kvh, int b, int q0, bool has_sink, float sink_l2, bf16_t* __restrict__ Y, int ycol) {
;     ...
;     if (__any((it == 0) || (mxb > 0x41000000))) {
;       float mx = -1e30f;
; #pragma unroll
;       for (int i = 0; i < 16; ++i) mx = fmaxf(mx, fmaxf(s0[i], s1[i]));
;       mx = fmaxf(mx, __shfl_xor(mx, 32, 64));
;       const float delta = (it == 0) ? mx : fmaxf(mx, 0.f);
;       const float alpha = (it == 0) ? 1.f : __builtin_amdgcn_exp2f(-delta);
;       m += delta;
;       lsum *= alpha;
; #pragma unroll
;       for (int i = 0; i < 16; ++i) { o0[i] *= alpha; o1[i] *= alpha; s0[i] -= delta; s1[i] -= delta; }
;     }
	v_max_f32_e32 v116, v34, v34
	v_max_f32_e32 v117, v50, v50
	v_max_f32_e32 v116, v117, v116
	v_max_f32_e32 v117, v35, v35
	v_max_f32_e32 v118, v51, v51
	v_max_f32_e32 v117, v118, v117
	s_mov_b32 s6, 0xf149f2ca
	v_max3_f32 v116, v116, s6, v117
	v_max_f32_e32 v117, v36, v36
	v_max_f32_e32 v118, v52, v52
	v_max_f32_e32 v117, v118, v117
	v_max_f32_e32 v118, v37, v37
	v_max_f32_e32 v119, v53, v53
	v_max_f32_e32 v118, v119, v118
	v_max3_f32 v116, v116, v117, v118
	v_max_f32_e32 v117, v38, v38
	v_max_f32_e32 v118, v54, v54
	v_max_f32_e32 v117, v118, v117
	v_max_f32_e32 v118, v39, v39
	v_max_f32_e32 v119, v55, v55
	v_max_f32_e32 v118, v119, v118
	v_max3_f32 v116, v116, v117, v118
	v_max_f32_e32 v117, v40, v40
	v_max_f32_e32 v118, v56, v56
	v_max_f32_e32 v117, v118, v117
	v_max_f32_e32 v118, v41, v41
	v_max_f32_e32 v119, v57, v57
	v_max_f32_e32 v118, v119, v118
	v_max3_f32 v116, v116, v117, v118
	v_max_f32_e32 v117, v42, v42
	v_max_f32_e32 v118, v58, v58
	v_max_f32_e32 v117, v118, v117
	v_max_f32_e32 v118, v43, v43
	v_max_f32_e32 v119, v59, v59
	v_max_f32_e32 v118, v119, v118
	v_max3_f32 v116, v116, v117, v118
	v_max_f32_e32 v117, v44, v44
	v_max_f32_e32 v118, v60, v60
	v_max_f32_e32 v117, v118, v117
	v_max_f32_e32 v118, v45, v45
	v_max_f32_e32 v119, v61, v61
	v_max_f32_e32 v118, v119, v118
	v_max3_f32 v116, v116, v117, v118
	v_max_f32_e32 v117, v46, v46
	v_max_f32_e32 v118, v62, v62
	v_max_f32_e32 v117, v118, v117
	v_max_f32_e32 v118, v47, v47
	v_max_f32_e32 v119, v63, v63
	v_max_f32_e32 v118, v119, v118
	v_max3_f32 v116, v116, v117, v118
	v_max_f32_e32 v117, v48, v48
	v_max_f32_e32 v118, v64, v64
	v_max_f32_e32 v117, v118, v117
	v_max_f32_e32 v118, v49, v49
	v_max_f32_e32 v119, v65, v65
	v_max_f32_e32 v118, v119, v118
	v_max3_f32 v116, v116, v117, v118
	ds_bpermute_b32 v117, v109, v116
	s_waitcnt lgkmcnt(0)
	v_max3_f32 v117, v116, v117, 0
	v_exp_f32_e64 v116, -v117
	v_add_f32_e32 v111, v111, v117
	v_sub_f32_e32 v65, v65, v117
	v_sub_f32_e32 v64, v64, v117
	v_pk_mul_f32 v[32:33], v[32:33], v[116:117] op_sel_hi:[1,0]
	v_pk_mul_f32 v[30:31], v[30:31], v[116:117] op_sel_hi:[1,0]
	v_pk_mul_f32 v[28:29], v[28:29], v[116:117] op_sel_hi:[1,0]
	v_pk_mul_f32 v[26:27], v[26:27], v[116:117] op_sel_hi:[1,0]
	v_pk_mul_f32 v[24:25], v[24:25], v[116:117] op_sel_hi:[1,0]
	v_pk_mul_f32 v[22:23], v[22:23], v[116:117] op_sel_hi:[1,0]
	v_pk_mul_f32 v[20:21], v[20:21], v[116:117] op_sel_hi:[1,0]
	v_pk_mul_f32 v[18:19], v[18:19], v[116:117] op_sel_hi:[1,0]
	v_pk_mul_f32 v[16:17], v[16:17], v[116:117] op_sel_hi:[1,0]
	v_pk_mul_f32 v[14:15], v[14:15], v[116:117] op_sel_hi:[1,0]
	v_pk_mul_f32 v[12:13], v[12:13], v[116:117] op_sel_hi:[1,0]
	v_pk_mul_f32 v[10:11], v[10:11], v[116:117] op_sel_hi:[1,0]
	v_pk_mul_f32 v[8:9], v[8:9], v[116:117] op_sel_hi:[1,0]
	v_pk_mul_f32 v[6:7], v[6:7], v[116:117] op_sel_hi:[1,0]
	v_pk_mul_f32 v[4:5], v[4:5], v[116:117] op_sel_hi:[1,0]
	v_pk_mul_f32 v[2:3], v[2:3], v[116:117] op_sel_hi:[1,0]
	v_sub_f32_e32 v63, v63, v117
	v_sub_f32_e32 v62, v62, v117
	v_sub_f32_e32 v61, v61, v117
	v_sub_f32_e32 v60, v60, v117
	v_sub_f32_e32 v59, v59, v117
	v_sub_f32_e32 v58, v58, v117
	v_sub_f32_e32 v57, v57, v117
	v_sub_f32_e32 v56, v56, v117
	v_sub_f32_e32 v55, v55, v117
	v_sub_f32_e32 v54, v54, v117
	v_sub_f32_e32 v53, v53, v117
	v_sub_f32_e32 v52, v52, v117
	v_sub_f32_e32 v51, v51, v117
	v_sub_f32_e32 v50, v50, v117
	v_sub_f32_e32 v49, v49, v117
	v_sub_f32_e32 v48, v48, v117
	v_sub_f32_e32 v47, v47, v117
	v_sub_f32_e32 v46, v46, v117
	v_sub_f32_e32 v45, v45, v117
	v_sub_f32_e32 v44, v44, v117
	v_sub_f32_e32 v43, v43, v117
	v_sub_f32_e32 v42, v42, v117
	v_sub_f32_e32 v41, v41, v117
	v_sub_f32_e32 v40, v40, v117
	v_sub_f32_e32 v39, v39, v117
	v_sub_f32_e32 v38, v38, v117
	v_sub_f32_e32 v37, v37, v117
	v_sub_f32_e32 v36, v36, v117
	v_sub_f32_e32 v35, v35, v117
	v_sub_f32_e32 v34, v34, v117
	v_mul_f32_e32 v112, v112, v116
	s_branch .LBB0_150

; #define MFMA32(a, b, c) __builtin_amdgcn_mfma_f32_32x32x16_bf16((a), (b), (c), 0, 0, 0)
; #define ALOAD(i) { const int kk0 = TILE_K0(i); \
;     kr0 = *(const uint4*)(Kb + (size_t)(kk0 + krow0) * DQK + kcc0 * 8); \
;     if (K2) kr1 = *(const uint4*)(Kb + (size_t)(kk0 + krow1) * DQK + kcc1 * 8); \
;     vr0 = *(const uint4*)(Vb + (size_t)vrow0 * TT + kk0 + vcc0 * 8); }
; #define ASTORE(bb) { bf16_t* dK = (bf16_t*)smem + (bb) * BUFE; bf16_t* dV = dK + 64 * KSTR; \
;     *(uint4*)(dK + krow0 * KSTR + kcc0 * 8) = kr0; \
;     if (K2) *(uint4*)(dK + krow1 * KSTR + kcc1 * 8) = kr1; \
;     *(uint4*)(dV + vrow0 * VSTR + vcc0 * 8) = vr0; }
; #define ALOAD(i) { const int kk0 = (i) * 64; \
;     kr0 = *(const uint4*)(Kb + (size_t)(kk0 + krow0) * DQK + kcc0 * 8); \
;     if (K2) kr1 = *(const uint4*)(Kb + (size_t)(kk0 + krow1) * DQK + kcc1 * 8); \
;     vr0 = *(const uint4*)(Vb + (size_t)vrow0 * TT + kk0 + vcc0 * 8); }
; #define ASTORE(bb) { bf16_t* dK = (bf16_t*)smem + (bb) * BUFE; bf16_t* dV = dK + 64 * KSTR; \
;     *(uint4*)(dK + krow0 * KSTR + kcc0 * 8) = kr0; \
;     if (K2) *(uint4*)(dK + krow1 * KSTR + kcc1 * 8) = kr1; \
;     *(uint4*)(dV + vrow0 * VSTR + vcc0 * 8) = vr0; }
; template <int DQK, bool WINDOW>
; DI void attn_item(char* smem, const bf16_t* __restrict__ Q, const bf16_t* __restrict__ K, const bf16_t* __restrict__ VT,
;                   int qh, int kvh, int b, int q0, bool has_sink, float sink_l2, bf16_t* __restrict__ Y, int ycol) {
;     ...
;   for (int it = 0; it < ntiles; ++it) {
;     const int k0 = TILE_K0(it);
;     __syncthreads();
;     ASTORE((it + 1) & 1)
;     __builtin_amdgcn_sched_barrier(0);
;     ALOAD(min(it + 2, ntiles - 1))
;     __builtin_amdgcn_sched_barrier(0);
;     sK = (bf16_t*)smem + (it & 1) * BUFE;
;     sV = sK + 64 * KSTR;
;     f32x16 s0, s1;
;     const float ninit = -m;
; #pragma unroll
;     for (int i = 0; i < 16; ++i) { s0[i] = ninit; s1[i] = ninit; }
; #pragma unroll
;     for (int ks = 0; ks < KS; ++ks) {
;       bf16x8 a0 = *(const bf16x8*)(sK + r * KSTR + ks * 16 + 8 * h);
;       bf16x8 a1 = *(const bf16x8*)(sK + (32 + r) * KSTR + ks * 16 + 8 * h);
;       s0 = MFMA32(a0, qf[ks], s0);
;       s1 = MFMA32(a1, qf[ks], s1);
;     }
.LBB0_242:
	s_cmp_gt_u32 s4, 3
	s_cselect_b32 s5, s3, 0
	s_add_i32 s14, s4, 1
	s_bitcmp1_b32 s14, 0
	s_cselect_b32 s15, 0x4800, 0
	s_add_i32 s15, s15, 0
	v_lshlrev_b32_e32 v34, 1, v94
	v_add3_u32 v34, s15, v91, v34
	s_waitcnt lgkmcnt(0)
	s_barrier
	s_waitcnt vmcnt(0)
	ds_write_b128 v34, v[86:89]
	v_add3_u32 v34, s15, v93, v190
	ds_write_b128 v34, v[82:85] offset:9216
	s_add_i32 s15, s4, 2
	s_min_i32 s15, s15, s12
	s_lshl_b32 s16, s15, 6
	s_cmp_gt_i32 s15, 3
	s_cselect_b32 s15, s3, 0
	s_add_i32 s16, s15, s16
	v_add_u32_e32 v34, s16, v92
	v_ashrrev_i32_e32 v35, 31, v34
	v_lshlrev_b64 v[34:35], 7, v[34:35]
	v_lshl_add_u64 v[34:35], v[98:99], 0, v[34:35]
	s_ashr_i32 s17, s16, 31
	global_load_dwordx4 v[86:89], v[34:35], off
	v_lshl_add_u64 v[34:35], s[16:17], 1, v[96:97]
	global_load_dwordx4 v[82:85], v[34:35], off
	s_bitcmp1_b32 s4, 0
	s_cselect_b32 s15, 0x4800, 0
	v_add_u32_e32 v108, s15, v106
	v_lshl_add_u32 v109, v95, 1, v108
	ds_read_b128 v[110:113], v109
	v_xor_b32_e32 v34, 0x80000000, v103
	v_mov_b32_e32 v35, v34
	v_pk_mov_b32 v[36:37], v[34:35], v[34:35] op_sel:[0,0] op_sel_hi:[0,0]
	v_pk_mov_b32 v[38:39], v[34:35], v[34:35] op_sel:[0,0] op_sel_hi:[0,0]
	v_pk_mov_b32 v[40:41], v[34:35], v[34:35] op_sel:[0,0] op_sel_hi:[0,0]
	v_pk_mov_b32 v[42:43], v[34:35], v[34:35] op_sel:[0,0] op_sel_hi:[0,0]
	v_pk_mov_b32 v[44:45], v[34:35], v[34:35] op_sel:[0,0] op_sel_hi:[0,0]
	v_pk_mov_b32 v[46:47], v[34:35], v[34:35] op_sel:[0,0] op_sel_hi:[0,0]
	v_pk_mov_b32 v[48:49], v[34:35], v[34:35] op_sel:[0,0] op_sel_hi:[0,0]
	s_add_i32 s15, s5, s2
	s_cmpk_lt_i32 s15, 0x100
	s_waitcnt lgkmcnt(0)
	v_mfma_f32_32x32x16_bf16 v[50:65], v[110:113], v[66:69], v[34:49]
	ds_read_b128 v[110:113], v109 offset:4608
	s_waitcnt lgkmcnt(0)
	v_mfma_f32_32x32x16_bf16 v[34:49], v[110:113], v[66:69], v[34:49]
	ds_read_b128 v[110:113], v109 offset:32
	s_waitcnt lgkmcnt(0)
	v_mfma_f32_32x32x16_bf16 v[50:65], v[110:113], v[70:73], v[50:65]
	ds_read_b128 v[110:113], v109 offset:4640
	s_waitcnt lgkmcnt(0)
	v_mfma_f32_32x32x16_bf16 v[34:49], v[110:113], v[70:73], v[34:49]
	ds_read_b128 v[110:113], v109 offset:64
	s_waitcnt lgkmcnt(0)
	v_mfma_f32_32x32x16_bf16 v[50:65], v[110:113], v[74:77], v[50:65]
	ds_read_b128 v[110:113], v109 offset:4672
	s_waitcnt lgkmcnt(0)
	v_mfma_f32_32x32x16_bf16 v[34:49], v[110:113], v[74:77], v[34:49]
	ds_read_b128 v[110:113], v109 offset:96
	s_waitcnt lgkmcnt(0)
	v_mfma_f32_32x32x16_bf16 v[50:65], v[110:113], v[78:81], v[50:65]
	ds_read_b128 v[110:113], v109 offset:4704
	s_waitcnt lgkmcnt(0)
	v_mfma_f32_32x32x16_bf16 v[34:49], v[110:113], v[78:81], v[34:49]
	s_cbranch_scc1 .LBB0_244
; DI int crow(int reg, int h) { return (reg & 3) + 8 * (reg >> 2) + 4 * h; }
; template <int DQK, bool WINDOW>
; DI void attn_item(char* smem, const bf16_t* __restrict__ Q, const bf16_t* __restrict__ K, const bf16_t* __restrict__ VT,
;                   int qh, int kvh, int b, int q0, bool has_sink, float sink_l2, bf16_t* __restrict__ Y, int ycol) {
;     ...
;     if (WINDOW && k0 >= CTXL) {
; #pragma unroll
;       for (int i = 0; i < 16; ++i) {
;         const int kp = k0 + crow(i, h);
;         if (abs(qpos - kp) > 128) s0[i] = -1e30f;
;         if (abs(qpos - kp - 32) > 128) s1[i] = -1e30f;
;       }
;     }
	v_subrev_u32_e32 v109, s5, v107
	v_add_u32_e32 v110, 59, v109
	v_sub_u32_e32 v111, 0xffffffc5, v109
	v_max_i32_e32 v110, v110, v111
	v_cmp_gt_u32_e32 vcc, s33, v110
	v_add_u32_e32 v110, 27, v109
	v_sub_u32_e32 v111, 0xffffffe5, v109
	v_max_i32_e32 v110, v110, v111
	v_cndmask_b32_e32 v50, v246, v50, vcc
	v_cmp_gt_u32_e32 vcc, s33, v110
	v_add_u32_e32 v110, 58, v109
	v_sub_u32_e32 v111, 0xffffffc6, v109
	v_max_i32_e32 v110, v110, v111
	v_cndmask_b32_e32 v34, v246, v34, vcc
	v_cmp_gt_u32_e32 vcc, s33, v110
	v_add_u32_e32 v110, 26, v109
	v_sub_u32_e32 v111, 0xffffffe6, v109
	v_max_i32_e32 v110, v110, v111
	v_cndmask_b32_e32 v51, v246, v51, vcc
	v_cmp_gt_u32_e32 vcc, s33, v110
	v_add_u32_e32 v110, 57, v109
	v_sub_u32_e32 v111, 0xffffffc7, v109
	v_max_i32_e32 v110, v110, v111
	v_cndmask_b32_e32 v35, v246, v35, vcc
	v_cmp_gt_u32_e32 vcc, s33, v110
	v_add_u32_e32 v110, 25, v109
	v_sub_u32_e32 v111, 0xffffffe7, v109
	v_max_i32_e32 v110, v110, v111
	v_cndmask_b32_e32 v52, v246, v52, vcc
	v_cmp_gt_u32_e32 vcc, s33, v110
	v_add_u32_e32 v110, 56, v109
	v_sub_u32_e32 v111, 0xffffffc8, v109
	v_max_i32_e32 v110, v110, v111
	v_cndmask_b32_e32 v36, v246, v36, vcc
	v_cmp_gt_u32_e32 vcc, s33, v110
	v_add_u32_e32 v110, 24, v109
	v_sub_u32_e32 v111, 0xffffffe8, v109
	v_max_i32_e32 v110, v110, v111
	v_cndmask_b32_e32 v53, v246, v53, vcc
	v_cmp_gt_u32_e32 vcc, s33, v110
	v_add_u32_e32 v110, 51, v109
	v_sub_u32_e32 v111, 0xffffffcd, v109
	v_max_i32_e32 v110, v110, v111
	v_cndmask_b32_e32 v37, v246, v37, vcc
	v_cmp_gt_u32_e32 vcc, s33, v110
	v_add_u32_e32 v110, 19, v109
	v_sub_u32_e32 v111, 0xffffffed, v109
	v_max_i32_e32 v110, v110, v111
	v_cndmask_b32_e32 v54, v246, v54, vcc
	v_cmp_gt_u32_e32 vcc, s33, v110
	v_add_u32_e32 v110, 50, v109
	v_sub_u32_e32 v111, 0xffffffce, v109
	v_max_i32_e32 v110, v110, v111
	v_cndmask_b32_e32 v38, v246, v38, vcc
	v_cmp_gt_u32_e32 vcc, s33, v110
	v_add_u32_e32 v110, 18, v109
	v_sub_u32_e32 v111, 0xffffffee, v109
	v_max_i32_e32 v110, v110, v111
	v_cndmask_b32_e32 v55, v246, v55, vcc
	v_cmp_gt_u32_e32 vcc, s33, v110
	v_add_u32_e32 v110, 49, v109
	v_sub_u32_e32 v111, 0xffffffcf, v109
	v_max_i32_e32 v110, v110, v111
	v_cndmask_b32_e32 v39, v246, v39, vcc
	v_cmp_gt_u32_e32 vcc, s33, v110
	v_add_u32_e32 v110, 17, v109
	v_sub_u32_e32 v111, 0xffffffef, v109
	v_max_i32_e32 v110, v110, v111
	v_cndmask_b32_e32 v56, v246, v56, vcc
	v_cmp_gt_u32_e32 vcc, s33, v110
	v_add_u32_e32 v110, 48, v109
	v_sub_u32_e32 v111, 0xffffffd0, v109
	v_max_i32_e32 v110, v110, v111
	v_cndmask_b32_e32 v40, v246, v40, vcc
	v_cmp_gt_u32_e32 vcc, s33, v110
	v_add_u32_e32 v110, 16, v109
	v_sub_u32_e32 v111, -16, v109
	v_max_i32_e32 v110, v110, v111
	v_cndmask_b32_e32 v57, v246, v57, vcc
	v_cmp_gt_u32_e32 vcc, s33, v110
	v_add_u32_e32 v110, 43, v109
	v_sub_u32_e32 v111, 0xffffffd5, v109
	v_max_i32_e32 v110, v110, v111
	v_cndmask_b32_e32 v41, v246, v41, vcc
	v_cmp_gt_u32_e32 vcc, s33, v110
	v_add_u32_e32 v110, 11, v109
	v_sub_u32_e32 v111, -11, v109
	v_max_i32_e32 v110, v110, v111
	v_cndmask_b32_e32 v58, v246, v58, vcc
	v_cmp_gt_u32_e32 vcc, s33, v110
	v_add_u32_e32 v110, 42, v109
	v_sub_u32_e32 v111, 0xffffffd6, v109
	v_max_i32_e32 v110, v110, v111
	v_cndmask_b32_e32 v42, v246, v42, vcc
	v_cmp_gt_u32_e32 vcc, s33, v110
	v_add_u32_e32 v110, 10, v109
	v_sub_u32_e32 v111, -10, v109
	v_max_i32_e32 v110, v110, v111
	v_cndmask_b32_e32 v59, v246, v59, vcc
	v_cmp_gt_u32_e32 vcc, s33, v110
	v_add_u32_e32 v110, 41, v109
	v_sub_u32_e32 v111, 0xffffffd7, v109
	v_max_i32_e32 v110, v110, v111
	v_cndmask_b32_e32 v43, v246, v43, vcc
	v_cmp_gt_u32_e32 vcc, s33, v110
	v_add_u32_e32 v110, 9, v109
	v_sub_u32_e32 v111, -9, v109
	v_max_i32_e32 v110, v110, v111
	v_cndmask_b32_e32 v60, v246, v60, vcc
	v_cmp_gt_u32_e32 vcc, s33, v110
	v_add_u32_e32 v110, 40, v109
	v_sub_u32_e32 v111, 0xffffffd8, v109
	v_max_i32_e32 v110, v110, v111
	v_cndmask_b32_e32 v44, v246, v44, vcc
	v_cmp_gt_u32_e32 vcc, s33, v110
	v_add_u32_e32 v110, 8, v109
	v_sub_u32_e32 v111, -8, v109
	v_max_i32_e32 v110, v110, v111
	v_cndmask_b32_e32 v61, v246, v61, vcc
	v_cmp_gt_u32_e32 vcc, s33, v110
	v_add_u32_e32 v110, 35, v109
	v_sub_u32_e32 v111, 0xffffffdd, v109
	v_max_i32_e32 v110, v110, v111
	v_cndmask_b32_e32 v45, v246, v45, vcc
	v_cmp_gt_u32_e32 vcc, s33, v110
	v_add_u32_e32 v110, 3, v109
	v_sub_u32_e32 v111, -3, v109
	v_max_i32_e32 v110, v110, v111
	v_cndmask_b32_e32 v62, v246, v62, vcc
	v_cmp_gt_u32_e32 vcc, s33, v110
	v_add_u32_e32 v110, 34, v109
	v_sub_u32_e32 v111, 0xffffffde, v109
	v_max_i32_e32 v110, v110, v111
	v_cndmask_b32_e32 v46, v246, v46, vcc
	v_cmp_gt_u32_e32 vcc, s33, v110
	v_add_u32_e32 v110, 2, v109
	v_sub_u32_e32 v111, -2, v109
	v_max_i32_e32 v110, v110, v111
	v_cndmask_b32_e32 v63, v246, v63, vcc
	v_cmp_gt_u32_e32 vcc, s33, v110
	v_add_u32_e32 v110, 33, v109
	v_sub_u32_e32 v111, 0xffffffdf, v109
	v_max_i32_e32 v110, v110, v111
	v_cndmask_b32_e32 v47, v246, v47, vcc
	v_cmp_gt_u32_e32 vcc, s33, v110
	v_add_u32_e32 v110, 1, v109
	v_not_b32_e32 v111, v109
	v_max_i32_e32 v110, v110, v111
	v_cndmask_b32_e32 v64, v246, v64, vcc
	v_cmp_gt_u32_e32 vcc, s33, v110
	v_add_u32_e32 v110, 32, v109
	v_sub_u32_e32 v111, 0xffffffe0, v109
	v_max_i32_e32 v110, v110, v111
	v_cndmask_b32_e32 v48, v246, v48, vcc
	v_cmp_gt_u32_e32 vcc, s33, v110
	v_sub_u32_e32 v110, 0, v109
	v_max_i32_e32 v109, v109, v110
	v_cndmask_b32_e32 v65, v246, v65, vcc
	v_cmp_gt_u32_e32 vcc, s33, v109
	s_nop 1
	v_cndmask_b32_e32 v49, v246, v49, vcc
